# SSD S1: second G tile's operand LDS reads (B tile, C rows, dt) issued before the first tile's work so its MFMAs do not wait on LDS; tile 2 hand-emitted with packed f32 epilogue
# baseline (speedup 1.0000x reference)
; __device__ __forceinline__ void ssd_item(const Args& a, LAS unsigned char* lds, int layer, bool is_sample, int b, int h, int seq_row0, int nchunks,
;                                          bf16_t* proj, float* ssq, const int tid) {
;     ...
;         {
;             float o[8];
; #pragma unroll
;             for (int i = 0; i < 8; ++i) o[i] = cb[i];
; #pragma unroll
;             for (int k = 0; k < 4; ++k) { const u32x4 w = *(const LAS u32x4*)(lds + L_XRAW + (lane + k) * P64 + wave * 16);
;                 o[0] += cw[k][0] * bflo(w.x); o[1] += cw[k][1] * bfhi(w.x); o[2] += cw[k][2] * bflo(w.y); o[3] += cw[k][3] * bfhi(w.y);
;                 o[4] += cw[k][4] * bflo(w.z); o[5] += cw[k][5] * bfhi(w.z); o[6] += cw[k][6] * bflo(w.w); o[7] += cw[k][7] * bfhi(w.w); }
; #pragma unroll
;             for (int i = 0; i < 8; ++i) *(LAS bf16_t*)(lds + L_XST + (wave * 8 + i) * P64 + lane * 2) = f2bf(siluf_(o[i]));
;         }
;         {
;             const int oc = tid & 15, tk = (tid >> 4) * 2;
;             const float a63s = acv[63]; const float wa = dtv[tk] * __builtin_amdgcn_exp2f(a63s - acv[tk]), wb = dtv[tk + 1] * __builtin_amdgcn_exp2f(a63s - acv[tk + 1]);
;             LAS unsigned char* d = lds + L_BWT + (oc * 8) * P64 + ((((tk >> 3) ^ ((oc >> 1) & 7)) << 4) | ((tk * 2) & 15));
;             *(LAS unsigned*)(d + 0 * P64) = pk2(bflo(bo0.x) * wa, bflo(bo1.x) * wb); *(LAS unsigned*)(d + 1 * P64) = pk2(bfhi(bo0.x) * wa, bfhi(bo1.x) * wb);
;             *(LAS unsigned*)(d + 2 * P64) = pk2(bflo(bo0.y) * wa, bflo(bo1.y) * wb); *(LAS unsigned*)(d + 3 * P64) = pk2(bfhi(bo0.y) * wa, bfhi(bo1.y) * wb);
;             *(LAS unsigned*)(d + 4 * P64) = pk2(bflo(bo0.z) * wa, bflo(bo1.z) * wb); *(LAS unsigned*)(d + 5 * P64) = pk2(bfhi(bo0.z) * wa, bfhi(bo1.z) * wb);
;             *(LAS unsigned*)(d + 6 * P64) = pk2(bflo(bo0.w) * wa, bflo(bo1.w) * wb); *(LAS unsigned*)(d + 7 * P64) = pk2(bfhi(bo0.w) * wa, bfhi(bo1.w) * wb);
;         }
;     ...
;             for (int ci = 0; ci < 2; ++ci) { const int cbk = (wave & 1) * 2 + ci; f32x4 acc = (f32x4){0.f, 0.f, 0.f, 0.f};
; #pragma unroll
;                 for (int ks = 0; ks < 4; ++ks) { const bf16x8 av = *(const LAS bf16x8*)(lds + L_CM + (16 * rb + fr) * P128 + (32 * ks + 8 * fq) * 2);
;                     const bf16x8 bv = *(const LAS bf16x8*)(lds + L_BM + (16 * cbk + fr) * P128 + (32 * ks + 8 * fq) * 2); acc = mfma16(av, bv, acc); }
.LBB0_570:
	ds_read_b128 v[176:179], v123
	ds_read_b128 v[180:183], v123 offset:144
	ds_read_b128 v[184:187], v123 offset:288
	ds_read_b128 v[188:191], v123 offset:432
	s_add_i32 s65, s15, 0
	s_add_i32 s65, s65, 0x1c73c
	v_mov_b32_e32 v148, s65
	v_add_u32_e32 v153, s15, v120
	v_add_u32_e32 v153, 0x1a640, v153
	v_add_u32_e32 v169, s15, v119
	v_add_u32_e32 v169, 0x1a640, v169
	ds_read_b32 v148, v148
	ds_read_b32 v150, v153
	ds_read_b32 v149, v153 offset:8192
	ds_read_b32 v152, v169
	ds_read_b32 v151, v169 offset:8192
	v_add_u32_e32 v164, v110, v192
	v_add_u32_e32 v165, s15, v117
	v_add_u32_e32 v109, v111, v192
	s_waitcnt lgkmcnt(8)
	v_lshlrev_b32_e32 v216, 16, v176
	v_and_b32_e32 v217, 0xffff0000, v176
	v_lshlrev_b32_e32 v218, 16, v177
	v_and_b32_e32 v219, 0xffff0000, v177
	v_lshlrev_b32_e32 v220, 16, v178
	v_and_b32_e32 v221, 0xffff0000, v178
	v_lshlrev_b32_e32 v222, 16, v179
	v_and_b32_e32 v223, 0xffff0000, v179
	v_pk_fma_f32 v[102:103], v[6:7], v[216:217], v[38:39]
	v_pk_fma_f32 v[156:157], v[8:9], v[218:219], v[40:41]
	v_pk_fma_f32 v[158:159], v[2:3], v[220:221], v[34:35]
	v_pk_fma_f32 v[160:161], v[4:5], v[222:223], v[36:37]
	s_waitcnt lgkmcnt(7)
	v_lshlrev_b32_e32 v216, 16, v180
	v_and_b32_e32 v217, 0xffff0000, v180
	v_lshlrev_b32_e32 v218, 16, v181
	v_and_b32_e32 v219, 0xffff0000, v181
	v_lshlrev_b32_e32 v220, 16, v182
	v_and_b32_e32 v221, 0xffff0000, v182
	v_lshlrev_b32_e32 v222, 16, v183
	v_and_b32_e32 v223, 0xffff0000, v183
	v_add_u32_e32 v153, 0x1a640, v165
	v_pk_fma_f32 v[102:103], v[10:11], v[216:217], v[102:103]
	v_pk_fma_f32 v[156:157], v[12:13], v[218:219], v[156:157]
	v_pk_fma_f32 v[158:159], v[14:15], v[220:221], v[158:159]
	v_pk_fma_f32 v[160:161], v[16:17], v[222:223], v[160:161]
	s_waitcnt lgkmcnt(6)
	v_lshlrev_b32_e32 v216, 16, v184
	v_and_b32_e32 v217, 0xffff0000, v184
	v_lshlrev_b32_e32 v218, 16, v185
	v_and_b32_e32 v219, 0xffff0000, v185
	v_lshlrev_b32_e32 v220, 16, v186
	v_and_b32_e32 v221, 0xffff0000, v186
	v_lshlrev_b32_e32 v222, 16, v187
	v_and_b32_e32 v223, 0xffff0000, v187
	v_pk_fma_f32 v[102:103], v[18:19], v[216:217], v[102:103]
	v_pk_fma_f32 v[156:157], v[20:21], v[218:219], v[156:157]
	v_pk_fma_f32 v[158:159], v[22:23], v[220:221], v[158:159]
	v_pk_fma_f32 v[160:161], v[24:25], v[222:223], v[160:161]
	s_waitcnt lgkmcnt(5)
	v_lshlrev_b32_e32 v216, 16, v188
	v_and_b32_e32 v217, 0xffff0000, v188
	v_lshlrev_b32_e32 v218, 16, v189
	v_and_b32_e32 v219, 0xffff0000, v189
	v_lshlrev_b32_e32 v220, 16, v190
	v_and_b32_e32 v221, 0xffff0000, v190
	v_lshlrev_b32_e32 v222, 16, v191
	v_and_b32_e32 v223, 0xffff0000, v191
	v_pk_fma_f32 v[102:103], v[26:27], v[216:217], v[102:103]
	v_pk_fma_f32 v[156:157], v[28:29], v[218:219], v[156:157]
	v_pk_fma_f32 v[158:159], v[30:31], v[220:221], v[158:159]
	v_pk_fma_f32 v[160:161], v[32:33], v[222:223], v[160:161]
	v_mul_f32_e32 v224, 0xbfb8aa3b, v102
	v_mul_f32_e32 v225, 0xbfb8aa3b, v103
	v_mul_f32_e32 v226, 0xbfb8aa3b, v156
	v_mul_f32_e32 v227, 0xbfb8aa3b, v157
	v_mul_f32_e32 v228, 0xbfb8aa3b, v158
	v_mul_f32_e32 v229, 0xbfb8aa3b, v159
	v_mul_f32_e32 v230, 0xbfb8aa3b, v160
	v_mul_f32_e32 v231, 0xbfb8aa3b, v161
	v_exp_f32_e32 v224, v224
	v_exp_f32_e32 v225, v225
	v_exp_f32_e32 v226, v226
	v_exp_f32_e32 v227, v227
	v_exp_f32_e32 v228, v228
	v_exp_f32_e32 v229, v229
	v_exp_f32_e32 v230, v230
	v_exp_f32_e32 v231, v231
	v_pk_add_f32 v[224:225], v[224:225], 1.0 op_sel_hi:[1,0]
	v_pk_add_f32 v[226:227], v[226:227], 1.0 op_sel_hi:[1,0]
	v_pk_add_f32 v[228:229], v[228:229], 1.0 op_sel_hi:[1,0]
	v_pk_add_f32 v[230:231], v[230:231], 1.0 op_sel_hi:[1,0]
	v_rcp_f32_e32 v224, v224
	v_rcp_f32_e32 v225, v225
	v_rcp_f32_e32 v226, v226
	v_rcp_f32_e32 v227, v227
	v_rcp_f32_e32 v228, v228
	v_rcp_f32_e32 v229, v229
	v_rcp_f32_e32 v230, v230
	v_rcp_f32_e32 v231, v231
	v_pk_mul_f32 v[102:103], v[102:103], v[224:225]
	v_pk_mul_f32 v[156:157], v[156:157], v[226:227]
	v_pk_mul_f32 v[158:159], v[158:159], v[228:229]
	v_pk_mul_f32 v[160:161], v[160:161], v[230:231]
	v_cvt_pk_bf16_f32 v232, v102, v103
	v_cvt_pk_bf16_f32 v233, v156, v157
	v_cvt_pk_bf16_f32 v234, v158, v159
	v_cvt_pk_bf16_f32 v235, v160, v161
	ds_write_b16 v124, v232
	ds_write_b16_d16_hi v124, v232 offset:144
	ds_write_b16 v124, v233 offset:288
	ds_write_b16_d16_hi v124, v233 offset:432
	ds_write_b16 v194, v234 offset:576
	ds_write_b16_d16_hi v194, v234 offset:720
	ds_write_b16 v194, v235 offset:864
	ds_write_b16_d16_hi v194, v235 offset:1008
	s_waitcnt lgkmcnt(12)
	s_waitcnt lgkmcnt(10)
	v_sub_f32_e32 v103, v148, v149
	s_waitcnt lgkmcnt(8)
	v_sub_f32_e32 v148, v148, v151
	v_exp_f32_e32 v103, v103
	v_exp_f32_e32 v148, v148
	v_mul_f32_e32 v102, v150, v103
	v_mul_f32_e32 v103, v152, v148
	v_add_u32_e32 v224, 0xd000, v125
	v_lshlrev_b32_e32 v216, 16, v58
	v_lshlrev_b32_e32 v217, 16, v62
	v_and_b32_e32 v218, 0xffff0000, v58
	v_and_b32_e32 v219, 0xffff0000, v62
	v_pk_mul_f32 v[216:217], v[102:103], v[216:217]
	v_pk_mul_f32 v[218:219], v[102:103], v[218:219]
	v_cvt_pk_bf16_f32 v220, v216, v217
	v_cvt_pk_bf16_f32 v221, v218, v219
	ds_write2_b32 v224, v220, v221 offset1:36
	v_lshlrev_b32_e32 v216, 16, v59
	v_lshlrev_b32_e32 v217, 16, v63
	v_and_b32_e32 v218, 0xffff0000, v59
	v_and_b32_e32 v219, 0xffff0000, v63
	v_pk_mul_f32 v[216:217], v[102:103], v[216:217]
	v_pk_mul_f32 v[218:219], v[102:103], v[218:219]
	v_cvt_pk_bf16_f32 v222, v216, v217
	v_cvt_pk_bf16_f32 v223, v218, v219
	ds_write2_b32 v224, v222, v223 offset0:72 offset1:108
	v_lshlrev_b32_e32 v216, 16, v60
	v_lshlrev_b32_e32 v217, 16, v64
	v_and_b32_e32 v218, 0xffff0000, v60
	v_and_b32_e32 v219, 0xffff0000, v64
	v_pk_mul_f32 v[216:217], v[102:103], v[216:217]
	v_pk_mul_f32 v[218:219], v[102:103], v[218:219]
	v_cvt_pk_bf16_f32 v220, v216, v217
	v_cvt_pk_bf16_f32 v221, v218, v219
	ds_write2_b32 v224, v220, v221 offset0:144 offset1:180
	v_lshlrev_b32_e32 v216, 16, v61
	v_lshlrev_b32_e32 v217, 16, v65
	v_and_b32_e32 v218, 0xffff0000, v61
	v_and_b32_e32 v219, 0xffff0000, v65
	v_pk_mul_f32 v[216:217], v[102:103], v[216:217]
	v_pk_mul_f32 v[218:219], v[102:103], v[218:219]
	v_cvt_pk_bf16_f32 v222, v216, v217
	v_cvt_pk_bf16_f32 v223, v218, v219
	ds_write2_b32 v224, v222, v223 offset0:216 offset1:252
	v_add_u32_e32 v113, v114, v192
	ds_read_b128 v[176:179], v113 offset:35840
	ds_read_b128 v[180:183], v113 offset:35904
	s_waitcnt lgkmcnt(13)
; #define LAS __attribute__((address_space(3)))
; __device__ __forceinline__ bf16_t f2bf(float f) { return (bf16_t)(pk2(f, 0.f) & 0xffffu); }
; __device__ __forceinline__ f32x4 mfma16(bf16x8 a, bf16x8 b, f32x4 c) { return __builtin_amdgcn_mfma_f32_16x16x32_bf16(a, b, c, 0, 0, 0); }
; #define LBAR() do { asm volatile("s_waitcnt lgkmcnt(0)" ::: "memory"); __builtin_amdgcn_s_barrier(); asm volatile("" ::: "memory"); } while (0)
; __device__ __forceinline__ void ssd_item(const Args& a, LAS unsigned char* lds, int layer, bool is_sample, int b, int h, int seq_row0, int nchunks,
;                                          bf16_t* proj, float* ssq, const int tid) {
;     ...
;         {
;             float al[4];
; #pragma unroll
;             for (int j = 0; j < 4; ++j) al[j] = acv[16 * rb + 4 * fq + j];
; #pragma unroll
;             for (int ci = 0; ci < 2; ++ci) { const int cbk = (wave & 1) * 2 + ci; f32x4 acc = (f32x4){0.f, 0.f, 0.f, 0.f};
; #pragma unroll
;                 for (int ks = 0; ks < 4; ++ks) { const bf16x8 av = *(const LAS bf16x8*)(lds + L_CM + (16 * rb + fr) * P128 + (32 * ks + 8 * fq) * 2);
;                     const bf16x8 bv = *(const LAS bf16x8*)(lds + L_BM + (16 * cbk + fr) * P128 + (32 * ks + 8 * fq) * 2); acc = mfma16(av, bv, acc); }
;                 const int s = 16 * cbk + fr; const float as = acv[s], ds = dtv[s];
; #pragma unroll
;                 for (int j = 0; j < 4; ++j) { const int l = 16 * rb + 4 * fq + j;
;                     const float gv = (s <= l) ? acc[j] * __builtin_amdgcn_exp2f(al[j] - as) * ds : 0.f;
;                     *(LAS bf16_t*)(lds + L_G + l * P64 + s * 2) = f2bf(gv); } }
;         }
;         LBAR();
;     ...
;             const float dec = __builtin_amdgcn_exp2f(acv[63]);
; #pragma unroll
;             for (int i = 0; i < 4; ++i) { st[i] = st[i] * dec;
; #pragma unroll
;                 for (int ks = 0; ks < 2; ++ks) { const bf16x8 av = *(const LAS bf16x8*)(lds + L_XST + (16 * pb + fr) * P64 + (32 * ks + 8 * fq) * 2);
;                     const bf16x8 bv = *(const LAS bf16x8*)(lds + L_BWT + (16 * (nb0 + i) + fr) * P64 + (((4 * ks + fq) ^ ((nb0 + i) & 7)) << 4)); st[i] = mfma16(bv, av, st[i]); } }
	ds_read_b128 v[184:187], v113 offset:35968
	s_waitcnt lgkmcnt(13)
	ds_read_b128 v[188:191], v113 offset:36032
	s_waitcnt lgkmcnt(13)
	ds_read_b128 v[232:235], v164 offset:18432
	s_waitcnt lgkmcnt(13)
	ds_read_b128 v[236:239], v164 offset:18496
	s_waitcnt lgkmcnt(13)
	ds_read_b128 v[240:243], v164 offset:18560
	s_waitcnt lgkmcnt(13)
	ds_read_b128 v[244:247], v164 offset:18624
	v_add_u32_e32 v215, 0x1a680, v165
	s_waitcnt lgkmcnt(13)
	ds_read_b32 v215, v215
	s_waitcnt lgkmcnt(8)
	ds_read_b128 v[58:61], v164 offset:18432
	v_add_u32_e32 v102, v111, v192
	ds_read_b128 v[62:65], v102 offset:35840
	ds_read_b128 v[148:151], v164 offset:18496
	ds_read_b128 v[152:155], v164 offset:18624
	s_waitcnt lgkmcnt(2)
	v_mfma_f32_16x16x32_bf16 v[58:61], v[58:61], v[62:65], 0
	ds_read_b128 v[62:65], v164 offset:18560
	ds_read_b128 v[156:159], v102 offset:35904
	ds_read_b128 v[160:163], v102 offset:35968
	v_add_u32_e32 v103, s15, v118
	v_add_u32_e32 v103, 0x1c640, v103
	s_waitcnt lgkmcnt(1)
	v_mfma_f32_16x16x32_bf16 v[58:61], v[148:151], v[156:159], v[58:61]
	ds_read_b128 v[148:151], v103
	v_add_u32_e32 v157, 0x1a640, v165
	v_add_u32_e32 v158, 0x1c680, v165
	s_waitcnt lgkmcnt(1)
	v_mfma_f32_16x16x32_bf16 v[58:61], v[62:65], v[160:163], v[58:61]
	v_add_u32_e32 v62, 0x1c640, v165
	ds_read_b32 v156, v62
	ds_read_b128 v[62:65], v102 offset:36032
	ds_read_b32 v102, v157
	ds_read_b32 v169, v158
	s_waitcnt lgkmcnt(2)
	v_mfma_f32_16x16x32_bf16 v[58:61], v[152:155], v[62:65], v[58:61]
	v_pk_add_f32 v[216:217], v[148:149], v[156:157] op_sel_hi:[1,0] neg_lo:[0,1] neg_hi:[0,1]
	v_pk_add_f32 v[218:219], v[150:151], v[156:157] op_sel_hi:[1,0] neg_lo:[0,1] neg_hi:[0,1]
	v_exp_f32_e32 v216, v216
	v_exp_f32_e32 v217, v217
	v_exp_f32_e32 v218, v218
	v_exp_f32_e32 v219, v219
	v_add_u32_e32 v63, v112, v195
	s_nop 2
	v_pk_mul_f32 v[58:59], v[58:59], v[216:217]
	v_pk_mul_f32 v[60:61], v[60:61], v[218:219]
	s_waitcnt lgkmcnt(1)
	v_pk_mul_f32 v[58:59], v[102:103], v[58:59] op_sel_hi:[0,1]
	v_pk_mul_f32 v[60:61], v[102:103], v[60:61] op_sel_hi:[0,1]
	v_cndmask_b32_e64 v58, v58, 0, s[40:41]
	v_cndmask_b32_e64 v59, v59, 0, s[42:43]
	v_cndmask_b32_e64 v60, v60, 0, s[44:45]
	v_cndmask_b32_e64 v61, v61, 0, s[46:47]
	v_cvt_pk_bf16_f32 v58, v58, v59
	v_cvt_pk_bf16_f32 v60, v60, v61
	ds_write_b16 v63, v58 offset:9216
	ds_write_b16_d16_hi v63, v58 offset:9360
	ds_write_b16 v63, v60 offset:9504
	ds_write_b16_d16_hi v63, v60 offset:9648
	s_waitcnt lgkmcnt(0)
	s_nop 1
	v_mfma_f32_16x16x32_bf16 v[156:159], v[232:235], v[176:179], 0
	v_mfma_f32_16x16x32_bf16 v[156:159], v[236:239], v[180:183], v[156:159]
	v_mfma_f32_16x16x32_bf16 v[156:159], v[240:243], v[184:187], v[156:159]
	v_mfma_f32_16x16x32_bf16 v[156:159], v[244:247], v[188:191], v[156:159]
	v_pk_add_f32 v[160:161], v[148:149], v[168:169] op_sel:[0,1] op_sel_hi:[1,1] neg_lo:[0,1] neg_hi:[0,1]
	v_pk_add_f32 v[162:163], v[150:151], v[168:169] op_sel:[0,1] op_sel_hi:[1,1] neg_lo:[0,1] neg_hi:[0,1]
	v_exp_f32_e32 v160, v160
	v_exp_f32_e32 v161, v161
	v_exp_f32_e32 v162, v162
	v_exp_f32_e32 v163, v163
	v_add_u32_e32 v109, v115, v195
	s_nop 0
	v_pk_mul_f32 v[156:157], v[156:157], v[160:161]
	v_pk_mul_f32 v[158:159], v[158:159], v[162:163]
	v_pk_mul_f32 v[156:157], v[214:215], v[156:157] op_sel:[1,0] op_sel_hi:[1,1]
	v_pk_mul_f32 v[158:159], v[214:215], v[158:159] op_sel:[1,0] op_sel_hi:[1,1]
	v_cndmask_b32_e64 v156, v156, 0, s[48:49]
	v_cndmask_b32_e64 v157, v157, 0, s[50:51]
	v_cndmask_b32_e64 v158, v158, 0, s[52:53]
	v_cndmask_b32_e64 v159, v159, 0, s[54:55]
	v_cvt_pk_bf16_f32 v156, v156, v157
	v_cvt_pk_bf16_f32 v158, v158, v159
	ds_write_b16 v109, v156 offset:9216
	ds_write_b16_d16_hi v109, v156 offset:9360
	ds_write_b16 v109, v158 offset:9504
	ds_write_b16_d16_hi v109, v158 offset:9648
	s_waitcnt lgkmcnt(0)
	s_barrier
	v_mov_b32_e32 v58, s65
	ds_read_b32 v102, v58
	ds_read_b128 v[148:151], v147
	ds_read_b128 v[176:179], v137 offset:53248
	ds_read_b128 v[180:183], v139 offset:53248
	ds_read_b128 v[184:187], v141 offset:53248
	ds_read_b128 v[188:191], v143 offset:53248
	ds_read_b128 v[152:155], v147 offset:64
	ds_read_b128 v[216:219], v138 offset:53248
	ds_read_b128 v[220:223], v140 offset:53248
	ds_read_b128 v[224:227], v142 offset:53248
	ds_read_b128 v[228:231], v144 offset:53248
	ds_read_b128 v[156:159], v147 offset:9216
	ds_read_b128 v[160:163], v147 offset:9280
	s_waitcnt lgkmcnt(12)
	v_exp_f32_e32 v102, v102
	s_nop 0
	v_pk_mul_f32 v[66:67], v[66:67], v[102:103] op_sel_hi:[1,0]
	v_pk_mul_f32 v[68:69], v[68:69], v[102:103] op_sel_hi:[1,0]
	v_pk_mul_f32 v[78:79], v[78:79], v[102:103] op_sel_hi:[1,0]
	v_pk_mul_f32 v[80:81], v[80:81], v[102:103] op_sel_hi:[1,0]
	v_pk_mul_f32 v[70:71], v[70:71], v[102:103] op_sel_hi:[1,0]
	v_pk_mul_f32 v[72:73], v[72:73], v[102:103] op_sel_hi:[1,0]
	v_pk_mul_f32 v[74:75], v[74:75], v[102:103] op_sel_hi:[1,0]
	v_pk_mul_f32 v[76:77], v[76:77], v[102:103] op_sel_hi:[1,0]
	s_waitcnt lgkmcnt(11)
	s_waitcnt lgkmcnt(10)
	v_mfma_f32_16x16x32_bf16 v[66:69], v[176:179], v[148:151], v[66:69]
	s_waitcnt lgkmcnt(9)
	v_mfma_f32_16x16x32_bf16 v[78:81], v[180:183], v[148:151], v[78:81]
	s_waitcnt lgkmcnt(8)
	v_mfma_f32_16x16x32_bf16 v[70:73], v[184:187], v[148:151], v[70:73]
	s_waitcnt lgkmcnt(7)
	v_mfma_f32_16x16x32_bf16 v[74:77], v[188:191], v[148:151], v[74:77]
	ds_read_b128 v[232:235], v164 offset:18432
	ds_read_b128 v[236:239], v164 offset:18496
	ds_read_b128 v[240:243], v164 offset:18560
	ds_read_b128 v[244:247], v164 offset:18624
	ds_read_b128 v[176:179], v127
	ds_read_b128 v[180:183], v127 offset:64
	ds_read_b128 v[184:187], v127 offset:128
	ds_read_b128 v[188:191], v127 offset:192
	s_waitcnt lgkmcnt(14)
; #define LAS __attribute__((address_space(3)))
; __device__ __forceinline__ bf16_t f2bf(float f) { return (bf16_t)(pk2(f, 0.f) & 0xffffu); }
; __device__ __forceinline__ float bflo(unsigned w) { return __uint_as_float(w << 16); }
; __device__ __forceinline__ float bfhi(unsigned w) { return __uint_as_float(w & 0xffff0000u); }
; __device__ __forceinline__ float bf2f(bf16_t h) { return __uint_as_float(((unsigned)h) << 16); }
; __device__ __forceinline__ float siluf_(float x) { return x * __builtin_amdgcn_rcpf(1.f + __expf(-x)); }
; __device__ __forceinline__ void ssd_item(const Args& a, LAS unsigned char* lds, int layer, bool is_sample, int b, int h, int seq_row0, int nchunks,
;                                          bf16_t* proj, float* ssq, const int tid) {
;     ...
;             float sq[4] = {0.f, 0.f, 0.f, 0.f}, el[4];
; #pragma unroll
;             for (int j = 0; j < 4; ++j) el[j] = __builtin_amdgcn_exp2f(acv[16 * rb + 4 * fq + j]);
; #pragma unroll
;             for (int ci = 0; ci < 2; ++ci) { const int cbk = (wave & 1) * 2 + ci; f32x4 acc = (f32x4){0.f, 0.f, 0.f, 0.f}, acp = (f32x4){0.f, 0.f, 0.f, 0.f};
; #pragma unroll
;                 for (int ks = 0; ks < 2; ++ks) { const bf16x8 av = *(const LAS bf16x8*)(lds + L_G + (16 * rb + fr) * P64 + (32 * ks + 8 * fq) * 2);
;                     const bf16x8 bv = *(const LAS bf16x8*)(lds + L_XST + (16 * cbk + fr) * P64 + (32 * ks + 8 * fq) * 2); acc = mfma16(av, bv, acc); }
; #pragma unroll
;                 for (int ks = 0; ks < 4; ++ks) { const bf16x8 av = *(const LAS bf16x8*)(lds + L_CM + (16 * rb + fr) * P128 + (32 * ks + 8 * fq) * 2);
;                     const bf16x8 bv = *(const LAS bf16x8*)(lds + L_ST + (16 * cbk + fr) * P128 + (32 * ks + 8 * fq) * 2); acp = mfma16(av, bv, acp); }
;                 const int p = 16 * cbk + fr;
;                 const u32x2 xs4 = *(const LAS u32x2*)(lds + L_XST + p * P64 + (16 * rb + 4 * fq) * 2);
;                 const float xsv[4] = {bflo(xs4.x), bfhi(xs4.x), bflo(xs4.y), bfhi(xs4.y)};
; #pragma unroll
;                 for (int j = 0; j < 4; ++j) { const int l = 16 * rb + 4 * fq + j;
;                     LAS bf16_t* zp = (LAS bf16_t*)(lds + L_ZT + l * P64 + p * 2);
;                     const float z = bf2f(*zp);
;                     const float yg = (acc[j] + el[j] * acp[j] + xsv[j] * dsk) * siluf_(z);
;                     *zp = f2bf(yg); sq[j] += yg * yg; } }
	s_waitcnt lgkmcnt(13)
	v_mfma_f32_16x16x32_bf16 v[66:69], v[216:219], v[152:155], v[66:69]
	s_waitcnt lgkmcnt(12)
	v_mfma_f32_16x16x32_bf16 v[78:81], v[220:223], v[152:155], v[78:81]
	s_waitcnt lgkmcnt(11)
	v_mfma_f32_16x16x32_bf16 v[70:73], v[224:227], v[152:155], v[70:73]
	s_waitcnt lgkmcnt(10)
	v_mfma_f32_16x16x32_bf16 v[74:77], v[228:231], v[152:155], v[74:77]
	ds_read_b128 v[148:151], v126
	ds_read_b128 v[152:155], v126 offset:64
	ds_read_b64 v[248:249], v128
	ds_read_b64 v[250:251], v128 offset:2304
	s_waitcnt lgkmcnt(7)
	v_mfma_f32_16x16x32_bf16 v[176:179], v[232:235], v[176:179], 0
	ds_read_b128 v[216:219], v131
	ds_read_b128 v[220:223], v131 offset:64
	ds_read_b128 v[224:227], v131 offset:128
	ds_read_b128 v[228:231], v131 offset:192
	ds_read_b128 v[58:61], v130
	ds_read_b128 v[62:65], v130 offset:64
	s_waitcnt lgkmcnt(12)
	v_mfma_f32_16x16x32_bf16 v[176:179], v[236:239], v[180:183], v[176:179]
	s_waitcnt lgkmcnt(11)
	v_mfma_f32_16x16x32_bf16 v[176:179], v[240:243], v[184:187], v[176:179]
	s_waitcnt lgkmcnt(10)
	v_mfma_f32_16x16x32_bf16 v[176:179], v[244:247], v[188:191], v[176:179]
	s_waitcnt lgkmcnt(9)
	v_mfma_f32_16x16x32_bf16 v[148:151], v[156:159], v[148:151], 0
	ds_read_u16 v165, v129
	ds_read_u16 v169, v129 offset:144
	ds_read_u16 v170, v129 offset:288
	ds_read_u16 v171, v129 offset:432
	s_waitcnt lgkmcnt(12)
	v_mfma_f32_16x16x32_bf16 v[148:151], v[160:163], v[152:155], v[148:151]
	s_waitcnt lgkmcnt(9)
	v_mfma_f32_16x16x32_bf16 v[216:219], v[232:235], v[216:219], 0
	ds_read_b128 v[232:235], v103
	ds_read_u16 v172, v132
	ds_read_u16 v173, v132 offset:144
	ds_read_u16 v215, v132 offset:288
	ds_read_u16 v102, v132 offset:432
	s_waitcnt lgkmcnt(13)
	v_mfma_f32_16x16x32_bf16 v[216:219], v[236:239], v[220:223], v[216:219]
	s_waitcnt lgkmcnt(10)
	v_mfma_f32_16x16x32_bf16 v[58:61], v[156:159], v[58:61], 0
	s_waitcnt lgkmcnt(9)
	v_mfma_f32_16x16x32_bf16 v[58:61], v[160:163], v[62:65], v[58:61]
	s_waitcnt lgkmcnt(4)
	v_exp_f32_e32 v232, v232
	v_exp_f32_e32 v233, v233
	v_exp_f32_e32 v234, v234
	v_exp_f32_e32 v235, v235
	v_mfma_f32_16x16x32_bf16 v[216:219], v[240:243], v[224:227], v[216:219]
	v_lshlrev_b32_e32 v180, 16, v248
	v_and_b32_e32 v181, 0xffff0000, v248
	v_lshlrev_b32_e32 v182, 16, v249
	v_and_b32_e32 v183, 0xffff0000, v249
	v_mfma_f32_16x16x32_bf16 v[216:219], v[244:247], v[228:231], v[216:219]
	v_lshlrev_b32_e32 v184, 16, v165
	v_lshlrev_b32_e32 v185, 16, v169
	v_lshlrev_b32_e32 v186, 16, v170
	v_lshlrev_b32_e32 v187, 16, v171
	v_mul_f32_e32 v188, 0xbfb8aa3b, v184
	v_mul_f32_e32 v189, 0xbfb8aa3b, v185
	v_mul_f32_e32 v190, 0xbfb8aa3b, v186
	v_mul_f32_e32 v191, 0xbfb8aa3b, v187
	v_exp_f32_e32 v188, v188
	v_exp_f32_e32 v189, v189
	v_exp_f32_e32 v190, v190
	v_exp_f32_e32 v191, v191
	v_pk_fma_f32 v[148:149], v[232:233], v[176:177], v[148:149]
	v_pk_fma_f32 v[150:151], v[234:235], v[178:179], v[150:151]
	v_pk_fma_f32 v[148:149], v[180:181], v[94:95], v[148:149] op_sel:[0,1,0] op_sel_hi:[1,1,1]
	v_pk_fma_f32 v[150:151], v[182:183], v[94:95], v[150:151] op_sel:[0,1,0] op_sel_hi:[1,1,1]
	v_pk_add_f32 v[188:189], v[188:189], 1.0 op_sel_hi:[1,0]
	v_pk_add_f32 v[190:191], v[190:191], 1.0 op_sel_hi:[1,0]
	v_rcp_f32_e32 v188, v188
	v_rcp_f32_e32 v189, v189
	v_rcp_f32_e32 v190, v190
	v_rcp_f32_e32 v191, v191
	v_pk_mul_f32 v[188:189], v[188:189], v[184:185]
	v_pk_mul_f32 v[190:191], v[190:191], v[186:187]
	v_pk_mul_f32 v[152:153], v[148:149], v[188:189]
	v_pk_mul_f32 v[154:155], v[150:151], v[190:191]
	v_cvt_pk_bf16_f32 v176, v152, v1
	ds_write_b16 v129, v176
	v_cvt_pk_bf16_f32 v177, v153, v1
	ds_write_b16 v129, v177 offset:144
	v_cvt_pk_bf16_f32 v178, v154, v1
	ds_write_b16 v129, v178 offset:288
	v_cvt_pk_bf16_f32 v179, v155, v1
	ds_write_b16 v129, v179 offset:432
	v_lshlrev_b32_e32 v184, 16, v250
	v_and_b32_e32 v185, 0xffff0000, v250
	v_lshlrev_b32_e32 v186, 16, v251
	v_and_b32_e32 v187, 0xffff0000, v251
	s_waitcnt lgkmcnt(7)
; #define LAS __attribute__((address_space(3)))
; __device__ __forceinline__ bf16_t f2bf(float f) { return (bf16_t)(pk2(f, 0.f) & 0xffffu); }
; __device__ __forceinline__ float bf2f(bf16_t h) { return __uint_as_float(((unsigned)h) << 16); }
; __device__ __forceinline__ float siluf_(float x) { return x * __builtin_amdgcn_rcpf(1.f + __expf(-x)); }
; __device__ __forceinline__ f32x4 mfma16(bf16x8 a, bf16x8 b, f32x4 c) { return __builtin_amdgcn_mfma_f32_16x16x32_bf16(a, b, c, 0, 0, 0); }
; #define LBAR() do { asm volatile("s_waitcnt lgkmcnt(0)" ::: "memory"); __builtin_amdgcn_s_barrier(); asm volatile("" ::: "memory"); } while (0)
; __device__ __forceinline__ void ssd_item(const Args& a, LAS unsigned char* lds, int layer, bool is_sample, int b, int h, int seq_row0, int nchunks,
;                                          bf16_t* proj, float* ssq, const int tid) {
;     ...
;                 for (int j = 0; j < 4; ++j) { const int l = 16 * rb + 4 * fq + j;
;                     LAS bf16_t* zp = (LAS bf16_t*)(lds + L_ZT + l * P64 + p * 2);
;                     const float z = bf2f(*zp);
;                     const float yg = (acc[j] + el[j] * acp[j] + xsv[j] * dsk) * siluf_(z);
;                     *zp = f2bf(yg); sq[j] += yg * yg; } }
; #pragma unroll
;             for (int j = 0; j < 4; ++j) { const float v = row16_sum(sq[j]);
;                 if (fr == 0) ssqp[(16 * rb + 4 * fq + j) * 2 + (wave & 1)] = v; }
;             const float dec = __builtin_amdgcn_exp2f(acv[63]);
; #pragma unroll
;             for (int i = 0; i < 4; ++i) { st[i] = st[i] * dec;
; #pragma unroll
;                 for (int ks = 0; ks < 2; ++ks) { const bf16x8 av = *(const LAS bf16x8*)(lds + L_XST + (16 * pb + fr) * P64 + (32 * ks + 8 * fq) * 2);
;                     const bf16x8 bv = *(const LAS bf16x8*)(lds + L_BWT + (16 * (nb0 + i) + fr) * P64 + (((4 * ks + fq) ^ ((nb0 + i) & 7)) << 4)); st[i] = mfma16(bv, av, st[i]); } }
;         }
;         LBAR();
;         if (tid < 64) ((LAS float*)(lds + L_SSQA))[c * 64 + tid] = ssqp[tid * 2] + ssqp[tid * 2 + 1];
	v_lshlrev_b32_e32 v180, 16, v172
	s_waitcnt lgkmcnt(6)
	v_lshlrev_b32_e32 v181, 16, v173
	s_waitcnt lgkmcnt(5)
	v_lshlrev_b32_e32 v182, 16, v215
	s_waitcnt lgkmcnt(4)
	v_lshlrev_b32_e32 v183, 16, v102
	v_mul_f32_e32 v188, 0xbfb8aa3b, v180
	v_mul_f32_e32 v189, 0xbfb8aa3b, v181
	v_mul_f32_e32 v190, 0xbfb8aa3b, v182
	v_mul_f32_e32 v191, 0xbfb8aa3b, v183
	v_exp_f32_e32 v188, v188
	v_exp_f32_e32 v189, v189
	v_exp_f32_e32 v190, v190
	v_exp_f32_e32 v191, v191
	v_pk_fma_f32 v[58:59], v[232:233], v[216:217], v[58:59]
	v_pk_fma_f32 v[60:61], v[234:235], v[218:219], v[60:61]
	v_pk_fma_f32 v[58:59], v[184:185], v[94:95], v[58:59] op_sel:[0,1,0] op_sel_hi:[1,1,1]
	v_pk_fma_f32 v[60:61], v[186:187], v[94:95], v[60:61] op_sel:[0,1,0] op_sel_hi:[1,1,1]
	v_pk_add_f32 v[188:189], v[188:189], 1.0 op_sel_hi:[1,0]
	v_pk_add_f32 v[190:191], v[190:191], 1.0 op_sel_hi:[1,0]
	v_rcp_f32_e32 v188, v188
	v_rcp_f32_e32 v189, v189
	v_rcp_f32_e32 v190, v190
	v_rcp_f32_e32 v191, v191
	v_pk_mul_f32 v[188:189], v[188:189], v[180:181]
	v_pk_mul_f32 v[190:191], v[190:191], v[182:183]
	v_pk_mul_f32 v[62:63], v[58:59], v[188:189]
	v_pk_mul_f32 v[64:65], v[60:61], v[190:191]
	v_cvt_pk_bf16_f32 v220, v62, v1
	ds_write_b16 v132, v220
	v_cvt_pk_bf16_f32 v221, v63, v1
	ds_write_b16 v132, v221 offset:144
	v_cvt_pk_bf16_f32 v222, v64, v1
	ds_write_b16 v132, v222 offset:288
	v_cvt_pk_bf16_f32 v223, v65, v1
	ds_write_b16 v132, v223 offset:432
	v_pk_mul_f32 v[156:157], v[62:63], v[62:63]
	v_pk_mul_f32 v[158:159], v[64:65], v[64:65]
	v_pk_fma_f32 v[156:157], v[152:153], v[152:153], v[156:157]
	v_pk_fma_f32 v[158:159], v[154:155], v[154:155], v[158:159]
	s_nop 0
	v_add_f32_dpp v156, v156, v156 quad_perm:[1,0,3,2] row_mask:0xf bank_mask:0xf bound_ctrl:1
	v_add_f32_dpp v157, v157, v157 quad_perm:[1,0,3,2] row_mask:0xf bank_mask:0xf bound_ctrl:1
	v_add_f32_dpp v158, v158, v158 quad_perm:[1,0,3,2] row_mask:0xf bank_mask:0xf bound_ctrl:1
	v_add_f32_dpp v159, v159, v159 quad_perm:[1,0,3,2] row_mask:0xf bank_mask:0xf bound_ctrl:1
	v_add_f32_dpp v156, v156, v156 quad_perm:[2,3,0,1] row_mask:0xf bank_mask:0xf bound_ctrl:1
	v_add_f32_dpp v157, v157, v157 quad_perm:[2,3,0,1] row_mask:0xf bank_mask:0xf bound_ctrl:1
	v_add_f32_dpp v158, v158, v158 quad_perm:[2,3,0,1] row_mask:0xf bank_mask:0xf bound_ctrl:1
	v_add_f32_dpp v159, v159, v159 quad_perm:[2,3,0,1] row_mask:0xf bank_mask:0xf bound_ctrl:1
	v_add_f32_dpp v156, v156, v156 row_half_mirror row_mask:0xf bank_mask:0xf bound_ctrl:1
	v_add_f32_dpp v157, v157, v157 row_half_mirror row_mask:0xf bank_mask:0xf bound_ctrl:1
	v_add_f32_dpp v158, v158, v158 row_half_mirror row_mask:0xf bank_mask:0xf bound_ctrl:1
	v_add_f32_dpp v159, v159, v159 row_half_mirror row_mask:0xf bank_mask:0xf bound_ctrl:1
	v_mov_b32_dpp v160, v156 row_mirror row_mask:0xf bank_mask:0xf bound_ctrl:1
	v_mov_b32_dpp v161, v157 row_mirror row_mask:0xf bank_mask:0xf bound_ctrl:1
	v_mov_b32_dpp v162, v158 row_mirror row_mask:0xf bank_mask:0xf bound_ctrl:1
	v_mov_b32_dpp v163, v159 row_mirror row_mask:0xf bank_mask:0xf bound_ctrl:1
	s_and_saveexec_b64 s[20:21], s[6:7]
	v_add_f32_e32 v156, v156, v160
	v_add_f32_e32 v157, v157, v161
	v_add_f32_e32 v158, v158, v162
	v_add_f32_e32 v159, v159, v163
	ds_write_b32 v133, v156
	ds_write_b32 v134, v157
	ds_write_b32 v135, v158
	ds_write_b32 v136, v159
	s_or_b64 exec, exec, s[20:21]
	s_waitcnt lgkmcnt(0)
	s_barrier
	s_and_saveexec_b64 s[20:21], s[38:39]
	s_cbranch_execz .LBB0_560
	s_nop 1
	ds_read_b64 v[58:59], v145
	v_add_u32_e32 v60, s15, v116
	s_waitcnt lgkmcnt(0)
	v_add_f32_e32 v58, v58, v59
	ds_write_b32 v60, v58
	s_branch .LBB0_560
